# dependency acquire: L1 invalidate issued before the panel-counter poll so its latency overlaps the poll
# baseline (speedup 1.0000x reference)
.LBB0_315:
	v_lshlrev_b32_e32 v2, 6, v0
	v_lshlrev_b32_e32 v3, 2, v0
	v_lshlrev_b32_e32 v195, 4, v0
	v_and_b32_e32 v214, 48, v0
	v_and_b32_e32 v2, 0x3c0, v2
	v_and_b32_e32 v3, 32, v3
	v_or_b32_e32 v212, 0x2000, v195
	v_and_b32_e32 v213, 15, v0
	s_andn2_b64 vcc, exec, s[0:1]
	v_bitop3_b32 v215, v2, v3, v214 bitop3:0x36
	s_cbranch_vccnz .LBB0_500
	s_cmp_eq_u64 s[86:87], 0
	s_cselect_b64 s[16:17], -1, 0
	s_cmp_eq_u32 s26, -1
	s_cselect_b64 s[0:1], -1, 0
	s_or_b64 s[0:1], s[16:17], s[0:1]
	s_mov_b32 s91, -1
	s_and_b64 vcc, exec, s[0:1]
	s_cbranch_vccnz .LBB0_333
	v_cmp_gt_u32_e32 vcc, 64, v0
	s_and_saveexec_b64 s[0:1], vcc
	s_cbranch_execz .LBB0_332
	s_lshl_b32 s6, s26, 6
	s_ashr_i32 s7, s6, 31
	s_lshl_b64 s[6:7], s[6:7], 2
	s_add_u32 s6, s2, s6
	s_addc_u32 s7, s3, s7
	s_mov_b32 s18, 1
	v_mov_b32_e32 v2, 0
	buffer_inv sc1
	s_branch .LBB0_320

.LBB0_331:
	s_waitcnt vmcnt(0)
	s_waitcnt vmcnt(0)

.LBB0_345:
	s_or_b64 exec, exec, s[50:51]
	s_cmp_lg_u32 s93, 42
	s_cselect_b64 s[50:51], -1, 0
	s_cmp_eq_u32 s88, s91
	s_cselect_b64 s[52:53], -1, 0
	s_or_b64 s[54:55], s[50:51], s[12:13]
	s_or_b64 s[52:53], s[54:55], s[52:53]
	s_and_b64 vcc, exec, s[52:53]
	s_cbranch_vccnz .LBB0_362
	s_and_saveexec_b64 s[52:53], s[6:7]
	s_cbranch_execz .LBB0_361
	s_mov_b32 s26, 1
	buffer_inv sc1
	s_branch .LBB0_349

.LBB0_576:
	s_add_u32 s95, s86, 0x1180000
	s_addc_u32 s63, s87, 0
	v_lshlrev_b32_e32 v195, 4, v0
	s_andn2_b64 vcc, exec, s[6:7]
	v_lshlrev_b32_e32 v212, 2, v0
	s_cbranch_vccnz .LBB0_832
	s_add_u32 s93, s86, 0x18800
	s_addc_u32 s88, s87, 0
	s_cmp_eq_u32 s2, -1
	s_cbranch_scc1 .LBB0_594
	v_cmp_gt_u32_e32 vcc, 64, v0
	s_and_saveexec_b64 s[0:1], vcc
	s_cbranch_execz .LBB0_593
	s_lshl_b32 s6, s2, 6
	s_ashr_i32 s7, s6, 31
	s_lshl_b64 s[6:7], s[6:7], 2
	s_add_u32 s6, s93, s6
	s_addc_u32 s7, s88, s7
	s_mov_b32 s3, 1
	v_mov_b32_e32 v2, 0
	buffer_inv sc1
	s_branch .LBB0_581

.LBB0_592:
	s_waitcnt vmcnt(0) lgkmcnt(0)
	s_waitcnt vmcnt(0)

.LBB0_616:
	s_cmp_lg_u32 s71, 14
	s_cselect_b64 s[22:23], -1, 0
	s_or_b64 s[24:25], s[10:11], s[22:23]
	s_cmp_eq_u32 s14, s2
	s_cselect_b64 s[26:27], -1, 0
	s_or_b64 s[24:25], s[24:25], s[26:27]
	s_and_b64 vcc, exec, s[24:25]
	s_cbranch_vccnz .LBB0_633
	s_and_saveexec_b64 s[2:3], s[6:7]
	s_cbranch_execz .LBB0_632
	s_mov_b32 s74, 1
	buffer_inv sc1
	s_branch .LBB0_620

.LBB0_1281:
	s_add_u32 s2, s86, 0xac68000
	s_addc_u32 s3, s87, 0
	v_lshlrev_b32_e32 v2, 6, v0
	v_lshlrev_b32_e32 v3, 2, v0
	s_add_u32 s10, s86, 0x15f28000
	v_lshlrev_b32_e32 v202, 4, v0
	v_and_b32_e32 v204, 48, v0
	v_and_b32_e32 v2, 0x3c0, v2
	v_and_b32_e32 v3, 32, v3
	s_addc_u32 s11, s87, 0
	v_and_b32_e32 v195, 15, v0
	v_or_b32_e32 v203, 0x2000, v202
	s_andn2_b64 vcc, exec, s[0:1]
	v_bitop3_b32 v205, v2, v3, v204 bitop3:0x36
	s_cbranch_vccnz .LBB0_1346
	s_add_u32 s33, s86, 0x21000
	s_addc_u32 s53, s87, 0
	s_cmp_eq_u32 s12, -1
	s_cbranch_scc1 .LBB0_1299
	v_cmp_gt_u32_e32 vcc, 64, v0
	s_and_saveexec_b64 s[0:1], vcc
	s_cbranch_execz .LBB0_1298
	s_lshl_b32 s14, s12, 6
	s_ashr_i32 s15, s14, 31
	s_lshl_b64 s[14:15], s[14:15], 2
	s_add_u32 s14, s33, s14
	s_addc_u32 s15, s53, s15
	s_mov_b32 s7, 1
	v_mov_b32_e32 v2, 0
	buffer_inv sc1
	s_branch .LBB0_1286

.LBB0_1317:
	s_cmp_lg_u32 s77, 6
	s_cselect_b64 s[42:43], -1, 0
	s_or_b64 s[46:47], s[26:27], s[42:43]
	s_cmp_eq_u32 s22, s12
	s_cselect_b64 s[48:49], -1, 0
	s_or_b64 s[46:47], s[46:47], s[48:49]
	s_and_b64 vcc, exec, s[46:47]
	s_cbranch_vccnz .LBB0_1334
	s_and_saveexec_b64 s[12:13], s[0:1]
	s_cbranch_execz .LBB0_1333
	s_mov_b32 s78, 1
	buffer_inv sc1
	s_branch .LBB0_1321

.LBB0_1464:
	s_andn2_b64 vcc, exec, s[0:1]
	s_cbranch_vccnz .LBB0_1645
	s_add_u32 s60, s86, 0x29800
	s_addc_u32 s61, s87, 0
	s_cmp_eq_u32 s16, -1
	s_cbranch_scc1 .LBB0_1482
	v_cmp_gt_u32_e32 vcc, 64, v0
	s_and_saveexec_b64 s[0:1], vcc
	s_cbranch_execz .LBB0_1481
	s_lshl_b32 s6, s16, 6
	s_ashr_i32 s7, s6, 31
	s_lshl_b64 s[6:7], s[6:7], 2
	s_add_u32 s6, s60, s6
	s_addc_u32 s7, s61, s7
	s_mov_b32 s15, 1
	v_mov_b32_e32 v2, 0
	buffer_inv sc1
	s_branch .LBB0_1469

.LBB0_1500:
	s_or_b64 exec, exec, s[12:13]
	s_cmp_lg_u32 s58, 14
	s_cselect_b64 s[12:13], -1, 0
	s_or_b64 s[50:51], s[30:31], s[12:13]
	s_cmp_eq_u32 s40, s16
	s_cselect_b64 s[52:53], -1, 0
	s_or_b64 s[50:51], s[50:51], s[52:53]
	s_and_b64 vcc, exec, s[50:51]
	s_cbranch_vccnz .LBB0_1517
	s_and_saveexec_b64 s[16:17], s[6:7]
	s_cbranch_execz .LBB0_1516
	s_mov_b32 s26, 1
	buffer_inv sc1
	s_branch .LBB0_1504

.LBB0_1657:
	v_lshlrev_b32_e32 v195, 4, v0
	s_andn2_b64 vcc, exec, s[0:1]
	v_lshlrev_b32_e32 v202, 2, v0
	s_cbranch_vccnz .LBB0_1722
	s_add_u32 s54, s86, 0x32000
	s_addc_u32 s55, s87, 0
	s_cmp_eq_u32 s12, -1
	s_cbranch_scc1 .LBB0_1675
	v_cmp_gt_u32_e32 vcc, 64, v0
	s_and_saveexec_b64 s[0:1], vcc
	s_cbranch_execz .LBB0_1674
	s_lshl_b32 s14, s12, 6
	s_ashr_i32 s15, s14, 31
	s_lshl_b64 s[14:15], s[14:15], 2
	s_add_u32 s14, s54, s14
	s_addc_u32 s15, s55, s15
	s_mov_b32 s11, 1
	v_mov_b32_e32 v2, 0
	buffer_inv sc1
	s_branch .LBB0_1662

.LBB0_1693:
	s_cmp_lg_u32 s77, 14
	s_cselect_b64 s[46:47], -1, 0
	s_or_b64 s[48:49], s[28:29], s[46:47]
	s_cmp_eq_u32 s24, s12
	s_cselect_b64 s[50:51], -1, 0
	s_or_b64 s[48:49], s[48:49], s[50:51]
	s_and_b64 vcc, exec, s[48:49]
	s_cbranch_vccnz .LBB0_1710
	s_and_saveexec_b64 s[12:13], s[0:1]
	s_cbranch_execz .LBB0_1709
	s_mov_b32 s78, 1
	buffer_inv sc1
	s_branch .LBB0_1697

.LBB0_2060:
	s_andn2_b64 vcc, exec, s[6:7]
	s_cbranch_vccnz .LBB0_2168
	s_add_u32 s33, s86, 0x3a800
	s_addc_u32 s58, s87, 0
	s_cmp_eq_u32 s14, -1
	s_cbranch_scc1 .LBB0_2078
	v_cmp_gt_u32_e32 vcc, 64, v0
	s_and_saveexec_b64 s[0:1], vcc
	s_cbranch_execz .LBB0_2077
	s_lshl_b32 s6, s14, 6
	s_ashr_i32 s7, s6, 31
	s_lshl_b64 s[6:7], s[6:7], 2
	s_add_u32 s6, s33, s6
	s_addc_u32 s7, s58, s7
	s_mov_b32 s13, 1
	v_mov_b32_e32 v2, 0
	buffer_inv sc1
	s_branch .LBB0_2065

.LBB0_2101:
	s_or_b64 exec, exec, s[50:51]
	s_cmp_lg_u32 s90, 14
	s_cselect_b64 s[50:51], -1, 0
	s_or_b64 s[52:53], s[38:39], s[50:51]
	s_cmp_eq_u32 s42, s14
	s_cselect_b64 s[54:55], -1, 0
	s_or_b64 s[52:53], s[52:53], s[54:55]
	s_and_b64 vcc, exec, s[52:53]
	s_cbranch_vccnz .LBB0_2118
	s_and_saveexec_b64 s[14:15], s[6:7]
	s_cbranch_execz .LBB0_2117
	s_mov_b32 s91, 1
	buffer_inv sc1
	s_branch .LBB0_2105

.LBB0_2180:
	s_andn2_b64 vcc, exec, s[0:1]
	s_cbranch_vccnz .LBB0_2365
	s_add_u32 s49, s86, 0x43000
	s_addc_u32 s50, s87, 0
	s_cmp_eq_u32 s51, -1
	s_cbranch_scc1 .LBB0_2198
	v_cmp_gt_u32_e32 vcc, 64, v0
	s_and_saveexec_b64 s[0:1], vcc
	s_cbranch_execz .LBB0_2197
	s_lshl_b32 s2, s51, 6
	s_ashr_i32 s3, s2, 31
	s_lshl_b64 s[2:3], s[2:3], 2
	s_add_u32 s2, s49, s2
	s_addc_u32 s3, s50, s3
	s_mov_b32 s16, 1
	v_mov_b32_e32 v2, 0
	buffer_inv sc1
	s_branch .LBB0_2185

.LBB0_2210:
	s_or_b64 exec, exec, s[14:15]
	s_cmp_lg_u32 s46, 42
	s_cselect_b64 s[14:15], -1, 0
	s_or_b64 s[38:39], s[26:27], s[14:15]
	s_cmp_eq_u32 s77, s51
	s_cselect_b64 s[40:41], -1, 0
	s_or_b64 s[38:39], s[38:39], s[40:41]
	s_and_b64 vcc, exec, s[38:39]
	s_cbranch_vccnz .LBB0_2227
	s_and_saveexec_b64 s[38:39], s[6:7]
	s_cbranch_execz .LBB0_2226
	s_mov_b32 s22, 1
	buffer_inv sc1
	s_branch .LBB0_2214
